# rowop kind1 loop software-pipelined: next row x/o loads prefetched one iteration ahead into spare VGPRs (clamped on last row), param loads hoisted before prefetch, waits recounted
# baseline (speedup 1.0000x reference)
.LBB0_31:
	v_readlane_b32 s0, v255, 9
	s_cmp_lt_u32 s0, 12
	s_cbranch_scc0 .LBB0_36
	s_lshl_b32 s2, s74, 2
	s_waitcnt vmcnt(6)
	v_add_u32_e32 v40, s2, v246
	s_movk_i32 s0, 0x200
	s_mov_b64 s[76:77], s[28:29]
	v_cmp_gt_i32_e32 vcc, s0, v40
	s_and_saveexec_b64 s[0:1], vcc
	v_readlane_b32 s20, v255, 11
	v_readlane_b32 s30, v255, 13
	v_readlane_b32 s21, v255, 12
	v_readlane_b32 s22, v255, 17
	v_readlane_b32 s23, v253, 42
	s_mov_b32 s24, 0x345d000
	s_mov_b32 s25, 0x800000
	s_movk_i32 s26, 0x1ff
	s_mov_b64 s[28:29], 0x1000
	v_readlane_b32 s31, v255, 14
	s_mov_b64 s[34:35], 0x345d000
	s_cbranch_execz .LBB0_35
	v_cmp_lt_i32_e32 vcc, v211, v210
	v_readlane_b32 s4, v253, 0
	v_readlane_b32 s5, v253, 1
	v_cndmask_b32_e32 v1, v209, v211, vcc
	v_cmp_lt_i32_e32 vcc, v212, v210
	v_lshlrev_b32_e32 v41, 2, v1
	v_lshlrev_b32_e32 v0, 2, v247
	v_cndmask_b32_e32 v1, v209, v212, vcc
	v_cmp_lt_i32_e32 vcc, v206, v210
	v_lshlrev_b32_e32 v42, 2, v1
	v_readlane_b32 s4, v253, 45
	v_cndmask_b32_e32 v1, v209, v206, vcc
	v_cmp_lt_i32_e32 vcc, v213, v210
	v_lshlrev_b32_e32 v43, 2, v1
	v_or_b32_e32 v2, 0x100, v0
	v_cndmask_b32_e32 v1, v209, v213, vcc
	v_cmp_lt_i32_e32 vcc, v216, v210
	s_waitcnt vmcnt(5)
	v_lshlrev_b32_e32 v44, 2, v1
	v_lshlrev_b32_e32 v192, 4, v247
	v_cndmask_b32_e32 v1, v209, v216, vcc
	v_cmp_lt_i32_e32 vcc, v217, v210
	v_lshlrev_b32_e32 v45, 2, v1
	v_readlane_b32 s16, v253, 12
	v_cndmask_b32_e32 v1, v209, v217, vcc
	v_lshlrev_b32_e32 v46, 2, v1
	v_add_u32_e32 v1, s2, v246
	v_readlane_b32 s17, v253, 13
	v_readlane_b32 s5, v253, 46
	v_add_u32_e32 v26, 0x4000, v1
	v_or_b32_e32 v4, 0x200, v0
	v_lshl_add_u64 v[16:17], s[16:17], 0, v[192:193]
	v_lshl_add_u64 v[18:19], s[4:5], 0, v[192:193]
	v_lshlrev_b32_e32 v192, 2, v2
	v_ashrrev_i32_e32 v27, 31, v26
	v_or_b32_e32 v6, 0x300, v0
	v_lshl_add_u64 v[20:21], s[4:5], 0, v[192:193]
	v_lshlrev_b32_e32 v192, 2, v4
	v_lshlrev_b64 v[8:9], 11, v[26:27]
	v_readlane_b32 s2, v253, 43
	v_lshl_add_u64 v[22:23], s[4:5], 0, v[192:193]
	v_lshlrev_b32_e32 v192, 2, v6
	v_lshl_or_b32 v8, v247, 3, v8
	v_readlane_b32 s3, v253, 44
	v_lshl_add_u64 v[24:25], s[4:5], 0, v[192:193]
	v_lshlrev_b32_e32 v192, 2, v0
	v_lshl_add_u64 v[28:29], s[2:3], 0, v[8:9]
	s_mov_b64 s[2:3], 0
	v_lshlrev_b32_e32 v30, 2, v2
	v_lshlrev_b32_e32 v32, 2, v4
	v_lshlrev_b32_e32 v34, 2, v6
	v_readlane_b32 s6, v253, 2
	v_readlane_b32 s7, v253, 3
	v_readlane_b32 s8, v253, 4
	v_readlane_b32 s9, v253, 5
	v_readlane_b32 s10, v253, 6
	v_readlane_b32 s11, v253, 7
	v_readlane_b32 s12, v253, 8
	v_readlane_b32 s13, v253, 9
	v_readlane_b32 s14, v253, 10
	v_readlane_b32 s15, v253, 11
	v_readlane_b32 s18, v253, 14
	v_readlane_b32 s19, v253, 15
	v_cmp_gt_i32_e32 vcc, 0, v40
	v_min_i32_e32 v0, 0x4000, v26
	v_mov_b32_e32 v2, s23
	v_mov_b32_e32 v3, s89
	v_ashrrev_i32_e32 v31, 13, v0
	v_cndmask_b32_e32 v1, 0, v27, vcc
	v_cndmask_b32_e32 v0, v40, v26, vcc
	v_cndmask_b32_e32 v3, v2, v3, vcc
	v_mov_b32_e32 v2, s22
	v_mov_b32_e32 v4, s88
	v_cndmask_b32_e32 v2, v2, v4, vcc
	v_lshlrev_b64 v[0:1], 12, v[0:1]
	v_lshl_add_u64 v[0:1], v[2:3], 0, v[0:1]
	v_lshl_add_u64 v[36:37], v[0:1], 0, v[192:193]
	global_load_dwordx4 v[180:183], v[36:37], off nt
	global_load_dwordx4 v[184:187], v[36:37], off offset:1024 nt
	global_load_dwordx4 v[188:191], v[36:37], off offset:2048 nt
	global_load_dwordx4 v[232:235], v[36:37], off offset:3072 nt
	global_load_dwordx2 v[236:237], v[28:29], off
	global_load_dwordx2 v[238:239], v[28:29], off offset:512
	global_load_dwordx2 v[240:241], v[28:29], off offset:1024
	global_load_dwordx2 v[242:243], v[28:29], off offset:1536
	s_waitcnt vmcnt(0)
.LBB0_34:
	v_cmp_gt_i32_e32 vcc, 0, v40
	v_min_i32_e32 v0, 0x4000, v26
	v_mov_b32_e32 v2, s23
	v_mov_b32_e32 v3, s89
	v_ashrrev_i32_e32 v31, 13, v0
	v_cndmask_b32_e32 v1, 0, v27, vcc
	v_cndmask_b32_e32 v0, v40, v26, vcc
	v_cndmask_b32_e32 v3, v2, v3, vcc
	v_mov_b32_e32 v2, s22
	v_mov_b32_e32 v4, s88
	v_cndmask_b32_e32 v2, v2, v4, vcc
	v_lshlrev_b64 v[0:1], 12, v[0:1]
	v_lshl_add_u64 v[0:1], v[2:3], 0, v[0:1]
	v_lshl_add_u64 v[36:37], v[0:1], 0, v[192:193]
	s_waitcnt vmcnt(8)
	v_mov_b32_e32 v12, v180
	v_mov_b32_e32 v13, v181
	v_mov_b32_e32 v14, v182
	v_mov_b32_e32 v15, v183
	v_mov_b32_e32 v8, v184
	v_mov_b32_e32 v9, v185
	v_mov_b32_e32 v10, v186
	v_mov_b32_e32 v11, v187
	v_mov_b32_e32 v4, v188
	v_mov_b32_e32 v5, v189
	v_mov_b32_e32 v6, v190
	v_mov_b32_e32 v7, v191
	v_mov_b32_e32 v0, v232
	v_mov_b32_e32 v1, v233
	v_mov_b32_e32 v2, v234
	v_mov_b32_e32 v3, v235
	v_mov_b32_e32 v56, v236
	v_mov_b32_e32 v57, v237
	v_mov_b32_e32 v64, v238
	v_mov_b32_e32 v65, v239
	v_mov_b32_e32 v72, v240
	v_mov_b32_e32 v73, v241
	v_mov_b32_e32 v80, v242
	v_mov_b32_e32 v81, v243
	v_mul_hi_i32_i24_e32 v39, 0x6000, v31
	v_mul_i32_i24_e32 v38, 0x6000, v31
	v_lshl_add_u64 v[38:39], s[90:91], 0, v[38:39]
	s_waitcnt vmcnt(3)
	v_lshl_add_u64 v[52:53], v[38:39], 0, v[192:193]
	v_lshl_add_u64 v[76:77], v[52:53], 0, s[34:35]
	v_add_co_u32_e32 v52, vcc, s24, v52
	global_load_dwordx4 v[48:51], v[16:17], off
	s_nop 0
	v_addc_co_u32_e32 v53, vcc, 0, v53, vcc
	global_load_dwordx4 v[52:55], v[52:53], off
	s_mov_b32 s4, 0xf823c000
	v_add_u32_e32 v40, s20, v40
	v_lshl_add_u64 v[26:27], v[26:27], 0, s[20:21]
	v_and_b32_e32 v39, 0xffff0000, v56
	v_and_b32_e32 v85, 0xffff0000, v64
	v_lshlrev_b32_e32 v38, 16, v56
	v_lshlrev_b32_e32 v84, 16, v64
	v_mov_b32_e32 v66, v39
	v_mov_b32_e32 v67, v85
	v_lshlrev_b32_e32 v82, 16, v57
	v_and_b32_e32 v87, 0xffff0000, v65
	v_lshlrev_b32_e32 v86, 16, v65
	v_mov_b32_e32 v64, v38
	v_mov_b32_e32 v65, v84
	v_pk_mul_f32 v[66:67], v[66:67], v[66:67]
	v_and_b32_e32 v83, 0xffff0000, v57
	global_load_dwordx4 v[56:59], v[16:17], off offset:1024
	global_load_dwordx4 v[60:63], v[76:77], off offset:1024
	v_pk_fma_f32 v[64:65], v[64:65], v[64:65], v[66:67]
	v_mov_b32_e32 v66, v82
	v_mov_b32_e32 v67, v86
	v_mov_b32_e32 v68, v83
	v_mov_b32_e32 v69, v87
	v_pk_fma_f32 v[64:65], v[66:67], v[66:67], v[64:65]
	v_and_b32_e32 v91, 0xffff0000, v72
	v_pk_fma_f32 v[88:89], v[68:69], v[68:69], v[64:65]
	global_load_dwordx4 v[64:67], v[16:17], off offset:2048
	global_load_dwordx4 v[68:71], v[76:77], off offset:2048
	v_lshlrev_b32_e32 v90, 16, v72
	v_and_b32_e32 v93, 0xffff0000, v73
	v_lshlrev_b32_e32 v92, 16, v73
	global_load_dwordx4 v[72:75], v[16:17], off offset:3072
	s_nop 0
	global_load_dwordx4 v[76:79], v[76:77], off offset:3072
	v_add_u32_e32 v41, 3, v31
	v_mul_hi_i32_i24_e32 v42, 0x6000, v41
	v_mul_i32_i24_e32 v43, 0x6000, v41
	v_mov_b32_e32 v44, v43
	v_mov_b32_e32 v45, v42
	v_lshl_add_u64 v[46:47], s[96:97], 0, v[44:45]
	v_lshl_add_u64 v[44:45], v[46:47], 0, s[28:29]
	v_lshl_add_u64 v[106:107], v[44:45], 0, v[192:193]
	v_lshl_add_u64 v[108:109], v[46:47], 0, v[192:193]
	global_load_dwordx4 v[116:119], v[18:19], off
	global_load_dwordx4 v[120:123], v[106:107], off
	global_load_dwordx4 v[124:127], v[108:109], off
	v_mov_b32_e32 v41, v193
	v_mov_b32_e32 v46, v30
	v_mov_b32_e32 v47, v41
	v_lshl_add_u64 v[110:111], v[44:45], 0, v[46:47]
	global_load_dwordx4 v[136:139], v[20:21], off
	global_load_dwordx4 v[140:143], v[110:111], off
	global_load_dwordx4 v[144:147], v[108:109], off offset:1024
	v_mov_b32_e32 v46, v193
	v_mov_b32_e32 v47, v193
	v_mov_b32_e32 v106, v32
	v_mov_b32_e32 v107, v46
	v_lshl_add_u64 v[148:149], v[44:45], 0, v[106:107]
	global_load_dwordx4 v[150:153], v[22:23], off
	global_load_dwordx4 v[154:157], v[148:149], off
	global_load_dwordx4 v[158:161], v[108:109], off offset:2048
	v_mov_b32_e32 v106, v34
	v_mov_b32_e32 v107, v47
	v_lshl_add_u64 v[162:163], v[44:45], 0, v[106:107]
	global_load_dwordx4 v[164:167], v[24:25], off
	global_load_dwordx4 v[168:171], v[162:163], off
	global_load_dwordx4 v[172:175], v[108:109], off offset:3072
	v_cmp_gt_i32_e32 vcc, 0, v40
	v_mov_b32_e32 v248, s23
	v_mov_b32_e32 v249, s89
	v_cndmask_b32_e32 v177, 0, v27, vcc
	v_cndmask_b32_e32 v176, v40, v26, vcc
	v_cndmask_b32_e32 v249, v248, v249, vcc
	v_mov_b32_e32 v248, s22
	v_mov_b32_e32 v178, s88
	v_cndmask_b32_e32 v248, v248, v178, vcc
	v_lshlrev_b64 v[176:177], 12, v[176:177]
	v_lshl_add_u64 v[176:177], v[248:249], 0, v[176:177]
	v_lshl_add_u64 v[176:177], v[176:177], 0, v[192:193]
	v_lshl_add_u64 v[224:225], v[28:29], 0, s[30:31]
	v_cmp_lt_i32_e32 vcc, s26, v40
	s_nop 1
	v_cndmask_b32_e32 v176, v176, v36, vcc
	v_cndmask_b32_e32 v177, v177, v37, vcc
	v_cndmask_b32_e32 v224, v224, v28, vcc
	v_cndmask_b32_e32 v225, v225, v29, vcc
	global_load_dwordx4 v[180:183], v[176:177], off nt
	global_load_dwordx4 v[184:187], v[176:177], off offset:1024 nt
	global_load_dwordx4 v[188:191], v[176:177], off offset:2048 nt
	global_load_dwordx4 v[232:235], v[176:177], off offset:3072 nt
	global_load_dwordx2 v[236:237], v[224:225], off
	global_load_dwordx2 v[238:239], v[224:225], off offset:512
	global_load_dwordx2 v[240:241], v[224:225], off offset:1024
	global_load_dwordx2 v[242:243], v[224:225], off offset:1536
	v_and_b32_e32 v95, 0xffff0000, v80
	v_lshlrev_b32_e32 v94, 16, v80
	v_mov_b32_e32 v98, v91
	v_mov_b32_e32 v99, v95
	v_and_b32_e32 v97, 0xffff0000, v81
	v_lshlrev_b32_e32 v96, 16, v81
	v_mov_b32_e32 v80, v90
	v_mov_b32_e32 v81, v94
	v_pk_mul_f32 v[98:99], v[98:99], v[98:99]
	v_mov_b32_e32 v100, v93
	v_pk_fma_f32 v[80:81], v[80:81], v[80:81], v[98:99]
	v_mov_b32_e32 v98, v92
	v_mov_b32_e32 v99, v96
	v_mov_b32_e32 v101, v97
	v_pk_fma_f32 v[80:81], v[98:99], v[98:99], v[80:81]
	v_add_f32_e32 v33, v88, v89
	v_pk_fma_f32 v[80:81], v[100:101], v[100:101], v[80:81]
	s_nop 0
	v_add_f32_e32 v33, v33, v80
	v_add_f32_e32 v33, v33, v81
	s_nop 0
	s_nop 1
	v_add_f32_dpp v33, v33, v33 quad_perm:[1,0,3,2] row_mask:0xf bank_mask:0xf
	s_nop 1
	v_add_f32_dpp v33, v33, v33 quad_perm:[2,3,0,1] row_mask:0xf bank_mask:0xf
	s_nop 1
	v_add_f32_dpp v33, v33, v33 row_half_mirror row_mask:0xf bank_mask:0xf
	s_nop 1
	v_add_f32_dpp v33, v33, v33 row_mirror row_mask:0xf bank_mask:0xf
	s_nop 1
	v_mov_b32_e32 v35, v33
	s_nop 1
	v_permlane16_swap_b32_e32 v33, v35
	s_nop 1
	v_add_f32_e32 v33, v33, v35
	s_nop 1
	v_mov_b32_e32 v35, v33
	s_nop 1
	v_permlane32_swap_b32_e32 v33, v35
	s_nop 1
	v_add_f32_e32 v33, v33, v35
	s_nop 1
	v_fmamk_f32 v33, v33, 0x3a800000, v219
	v_cmp_gt_f32_e32 vcc, s25, v33
	v_mul_f32_e32 v35, 0x4b800000, v33
	s_nop 0
	v_cndmask_b32_e32 v33, v33, v35, vcc
	v_rsq_f32_e32 v33, v33
	s_nop 0
	v_mul_f32_e32 v35, 0x45800000, v33
	v_cndmask_b32_e32 v80, v33, v35, vcc
	v_pk_mul_f32 v[38:39], v[80:81], v[38:39] op_sel_hi:[0,1]
	s_waitcnt vmcnt(27)
	v_pk_mul_f32 v[38:39], v[48:49], v[38:39]
	v_pk_mul_f32 v[48:49], v[80:81], v[82:83] op_sel_hi:[0,1]
	v_pk_mul_f32 v[50:51], v[50:51], v[48:49]
	s_waitcnt vmcnt(26)
	v_pk_fma_f32 v[48:49], v[52:53], v[38:39], v[12:13]
	v_pk_mul_f32 v[12:13], v[80:81], v[84:85] op_sel_hi:[0,1]
	v_pk_fma_f32 v[50:51], v[54:55], v[50:51], v[14:15]
	s_waitcnt vmcnt(25)
	v_pk_mul_f32 v[12:13], v[56:57], v[12:13]
	v_pk_mul_f32 v[14:15], v[80:81], v[86:87] op_sel_hi:[0,1]
	v_pk_mul_f32 v[14:15], v[58:59], v[14:15]
	s_waitcnt vmcnt(24)
	v_pk_fma_f32 v[8:9], v[60:61], v[12:13], v[8:9]
	v_pk_mul_f32 v[12:13], v[80:81], v[90:91] op_sel_hi:[0,1]
	v_pk_fma_f32 v[10:11], v[62:63], v[14:15], v[10:11]
	s_waitcnt vmcnt(23)
	v_pk_mul_f32 v[12:13], v[12:13], v[64:65]
	v_pk_mul_f32 v[14:15], v[80:81], v[92:93] op_sel_hi:[0,1]
	v_pk_mul_f32 v[14:15], v[14:15], v[66:67]
	s_waitcnt vmcnt(22)
	v_pk_fma_f32 v[4:5], v[12:13], v[68:69], v[4:5]
	v_pk_mul_f32 v[12:13], v[80:81], v[94:95] op_sel_hi:[0,1]
	v_pk_fma_f32 v[6:7], v[14:15], v[70:71], v[6:7]
	s_waitcnt vmcnt(21)
	v_pk_mul_f32 v[12:13], v[12:13], v[72:73]
	v_pk_mul_f32 v[14:15], v[80:81], v[96:97] op_sel_hi:[0,1]
	v_pk_mul_f32 v[14:15], v[14:15], v[74:75]
	s_waitcnt vmcnt(20)
	v_pk_fma_f32 v[0:1], v[12:13], v[76:77], v[0:1]
	v_add_u32_e32 v12, 3, v31
	v_pk_fma_f32 v[2:3], v[14:15], v[78:79], v[2:3]
	global_store_dwordx4 v[36:37], v[48:51], off nt
	global_store_dwordx4 v[36:37], v[8:11], off offset:1024 nt
	global_store_dwordx4 v[36:37], v[4:7], off offset:2048 nt
	global_store_dwordx4 v[36:37], v[0:3], off offset:3072 nt
	v_mul_hi_i32_i24_e32 v13, 0x6000, v12
	v_mul_i32_i24_e32 v12, 0x6000, v12
	v_mov_b32_e32 v36, v49
	v_mov_b32_e32 v37, v9
	v_lshl_add_u64 v[14:15], s[96:97], 0, v[12:13]
	v_mov_b32_e32 v12, v48
	v_mov_b32_e32 v13, v8
	v_pk_mul_f32 v[36:37], v[36:37], v[36:37]
	v_mov_b32_e32 v38, v5
	v_pk_fma_f32 v[12:13], v[12:13], v[12:13], v[36:37]
	v_mov_b32_e32 v36, v50
	v_mov_b32_e32 v37, v10
	v_pk_fma_f32 v[12:13], v[36:37], v[36:37], v[12:13]
	v_mov_b32_e32 v36, v51
	v_mov_b32_e32 v37, v11
	v_mov_b32_e32 v39, v1
	v_pk_fma_f32 v[12:13], v[36:37], v[36:37], v[12:13]
	v_mov_b32_e32 v36, v4
	v_mov_b32_e32 v37, v0
	v_pk_mul_f32 v[38:39], v[38:39], v[38:39]
	v_add_f32_e32 v12, v12, v13
	v_pk_fma_f32 v[36:37], v[36:37], v[36:37], v[38:39]
	v_mov_b32_e32 v38, v6
	v_mov_b32_e32 v39, v2
	v_pk_fma_f32 v[36:37], v[38:39], v[38:39], v[36:37]
	v_mov_b32_e32 v38, v7
	v_mov_b32_e32 v39, v3
	v_pk_fma_f32 v[36:37], v[38:39], v[38:39], v[36:37]
	s_nop 0
	v_add_f32_e32 v12, v12, v36
	v_add_f32_e32 v12, v12, v37
	v_lshl_add_u64 v[36:37], v[14:15], 0, s[28:29]
	v_lshl_add_u64 v[38:39], v[36:37], 0, v[192:193]
	v_lshl_add_u64 v[14:15], v[14:15], 0, v[192:193]
	v_mov_b32_e32 v38, v48
	v_mov_b32_e32 v39, v50
	v_mov_b32_e32 v50, v49
	s_nop 0
	s_nop 1
	v_add_f32_dpp v12, v12, v12 quad_perm:[1,0,3,2] row_mask:0xf bank_mask:0xf
	s_nop 1
	v_add_f32_dpp v12, v12, v12 quad_perm:[2,3,0,1] row_mask:0xf bank_mask:0xf
	s_nop 1
	v_add_f32_dpp v12, v12, v12 row_half_mirror row_mask:0xf bank_mask:0xf
	s_nop 1
	v_add_f32_dpp v12, v12, v12 row_mirror row_mask:0xf bank_mask:0xf
	s_nop 1
	v_mov_b32_e32 v13, v12
	s_nop 1
	v_permlane16_swap_b32_e32 v12, v13
	s_nop 1
	v_add_f32_e32 v12, v12, v13
	s_nop 1
	v_mov_b32_e32 v13, v12
	s_nop 1
	v_permlane32_swap_b32_e32 v12, v13
	s_nop 1
	v_add_f32_e32 v12, v12, v13
	s_nop 1
	v_fmamk_f32 v12, v12, 0x3a800000, v219
	v_cmp_gt_f32_e32 vcc, s25, v12
	v_mul_f32_e32 v13, 0x4b800000, v12
	s_waitcnt vmcnt(23)
	v_mov_b32_e32 v52, v116
	v_mov_b32_e32 v53, v117
	v_mov_b32_e32 v54, v118
	v_mov_b32_e32 v55, v119
	v_mov_b32_e32 v64, v52
	v_cndmask_b32_e32 v12, v12, v13, vcc
	v_rsq_f32_e32 v12, v12
	v_mov_b32_e32 v65, v54
	v_mov_b32_e32 v54, v53
	s_waitcnt vmcnt(21)
	v_mov_b32_e32 v56, v120
	v_mov_b32_e32 v57, v121
	v_mov_b32_e32 v58, v122
	v_mov_b32_e32 v59, v123
	v_mov_b32_e32 v60, v124
	v_mov_b32_e32 v61, v125
	v_mov_b32_e32 v62, v126
	v_mov_b32_e32 v63, v127
	v_mov_b32_e32 v67, v62
	v_mul_f32_e32 v13, 0x45800000, v12
	v_cndmask_b32_e32 v12, v12, v13, vcc
	v_pk_mul_f32 v[38:39], v[38:39], v[12:13] op_sel_hi:[1,0]
	v_pk_mul_f32 v[48:49], v[50:51], v[12:13] op_sel_hi:[1,0]
	v_pk_mul_f32 v[38:39], v[64:65], v[38:39]
	v_mov_b32_e32 v65, v58
	v_mov_b32_e32 v58, v57
	v_mov_b32_e32 v64, v56
	v_pk_mul_f32 v[48:49], v[54:55], v[48:49]
	v_pk_add_f32 v[50:51], v[58:59], 1.0 op_sel_hi:[1,0]
	v_mov_b32_e32 v62, v61
	v_pk_add_f32 v[64:65], v[64:65], 1.0 op_sel_hi:[1,0]
	v_mov_b32_e32 v66, v60
	v_pk_fma_f32 v[48:49], v[50:51], v[48:49], v[62:63]
	v_pk_fma_f32 v[38:39], v[64:65], v[38:39], v[66:67]
	v_and_b32_sdwa v33, v49, v218 dst_sel:DWORD dst_unused:UNUSED_PAD src0_sel:WORD_1 src1_sel:DWORD
	v_and_b32_sdwa v13, v39, v218 dst_sel:DWORD dst_unused:UNUSED_PAD src0_sel:WORD_1 src1_sel:DWORD
	v_cvt_pk_bf16_f32 v38, v38, v48
	v_add3_u32 v33, v49, v33, s80
	v_add3_u32 v13, v39, v13, s80
	v_and_b32_e32 v33, 0xffff0000, v33
	v_add_co_u32_e32 v48, vcc, s4, v28
	v_or_b32_sdwa v39, v33, v13 dst_sel:DWORD dst_unused:UNUSED_PAD src0_sel:DWORD src1_sel:WORD_1
	s_nop 0
	v_addc_co_u32_e32 v49, vcc, -1, v29, vcc
	global_store_dwordx2 v[48:49], v[38:39], off
	v_mov_b32_e32 v31, v193
	v_lshl_add_u64 v[38:39], v[36:37], 0, v[30:31]
	v_mov_b32_e32 v38, v8
	v_mov_b32_e32 v39, v10
	v_pk_mul_f32 v[38:39], v[38:39], v[12:13] op_sel_hi:[1,0]
	v_mov_b32_e32 v10, v9
	v_pk_mul_f32 v[8:9], v[10:11], v[12:13] op_sel_hi:[1,0]
	s_mov_b32 s4, 0xf823d000
	v_mov_b32_e32 v33, v193
	v_mov_b32_e32 v35, v193
	s_waitcnt vmcnt(21)
	v_mov_b32_e32 v48, v136
	v_mov_b32_e32 v49, v137
	v_mov_b32_e32 v50, v138
	v_mov_b32_e32 v51, v139
	v_mov_b32_e32 v60, v48
	v_mov_b32_e32 v61, v50
	v_pk_mul_f32 v[38:39], v[38:39], v[60:61]
	s_waitcnt vmcnt(20)
	v_mov_b32_e32 v52, v140
	v_mov_b32_e32 v53, v141
	v_mov_b32_e32 v54, v142
	v_mov_b32_e32 v55, v143
	v_mov_b32_e32 v60, v52
	v_mov_b32_e32 v61, v54
	v_pk_add_f32 v[60:61], v[60:61], 1.0 op_sel_hi:[1,0]
	s_waitcnt vmcnt(19)
	v_mov_b32_e32 v56, v144
	v_mov_b32_e32 v57, v145
	v_mov_b32_e32 v58, v146
	v_mov_b32_e32 v59, v147
	v_mov_b32_e32 v62, v56
	v_mov_b32_e32 v63, v58
	v_mov_b32_e32 v50, v49
	v_mov_b32_e32 v54, v53
	v_pk_fma_f32 v[38:39], v[38:39], v[60:61], v[62:63]
	v_pk_mul_f32 v[8:9], v[8:9], v[50:51]
	v_pk_add_f32 v[10:11], v[54:55], 1.0 op_sel_hi:[1,0]
	v_mov_b32_e32 v58, v57
	v_pk_fma_f32 v[8:9], v[8:9], v[10:11], v[58:59]
	v_and_b32_sdwa v11, v38, v218 dst_sel:DWORD dst_unused:UNUSED_PAD src0_sel:WORD_1 src1_sel:DWORD
	v_add3_u32 v13, v38, v11, s80
	v_and_b32_sdwa v31, v8, v218 dst_sel:DWORD dst_unused:UNUSED_PAD src0_sel:WORD_1 src1_sel:DWORD
	v_cvt_pk_bf16_f32 v11, v39, v9
	v_add3_u32 v8, v8, v31, s80
	v_and_b32_e32 v8, 0xffff0000, v8
	v_or_b32_sdwa v10, v8, v13 dst_sel:DWORD dst_unused:UNUSED_PAD src0_sel:DWORD src1_sel:WORD_1
	v_add_co_u32_e32 v8, vcc, s4, v28
	s_nop 1
	v_addc_co_u32_e32 v9, vcc, -1, v29, vcc
	global_store_dwordx2 v[8:9], v[10:11], off offset:-3584
	v_lshl_add_u64 v[10:11], v[36:37], 0, v[32:33]
	v_mov_b32_e32 v10, v4
	v_mov_b32_e32 v11, v6
	v_pk_mul_f32 v[10:11], v[10:11], v[12:13] op_sel_hi:[1,0]
	v_mov_b32_e32 v6, v5
	v_pk_mul_f32 v[4:5], v[6:7], v[12:13] op_sel_hi:[1,0]
	v_cmp_lt_i32_e32 vcc, s26, v40
	v_lshl_add_u64 v[28:29], v[28:29], 0, s[30:31]
	s_or_b64 s[2:3], vcc, s[2:3]
	s_waitcnt vmcnt(19)
	v_mov_b32_e32 v48, v150
	v_mov_b32_e32 v49, v151
	v_mov_b32_e32 v50, v152
	v_mov_b32_e32 v51, v153
	v_mov_b32_e32 v38, v48
	v_mov_b32_e32 v39, v50
	v_pk_mul_f32 v[10:11], v[10:11], v[38:39]
	s_waitcnt vmcnt(18)
	v_mov_b32_e32 v52, v154
	v_mov_b32_e32 v53, v155
	v_mov_b32_e32 v54, v156
	v_mov_b32_e32 v55, v157
	v_mov_b32_e32 v38, v52
	v_mov_b32_e32 v39, v54
	v_pk_add_f32 v[38:39], v[38:39], 1.0 op_sel_hi:[1,0]
	s_waitcnt vmcnt(17)
	v_mov_b32_e32 v56, v158
	v_mov_b32_e32 v57, v159
	v_mov_b32_e32 v58, v160
	v_mov_b32_e32 v59, v161
	v_mov_b32_e32 v60, v56
	v_mov_b32_e32 v61, v58
	v_mov_b32_e32 v50, v49
	v_mov_b32_e32 v54, v53
	v_pk_fma_f32 v[10:11], v[10:11], v[38:39], v[60:61]
	v_pk_mul_f32 v[4:5], v[4:5], v[50:51]
	v_pk_add_f32 v[6:7], v[54:55], 1.0 op_sel_hi:[1,0]
	v_mov_b32_e32 v58, v57
	v_pk_fma_f32 v[4:5], v[4:5], v[6:7], v[58:59]
	v_cvt_pk_bf16_f32 v4, v10, v4
	v_cvt_pk_bf16_f32 v5, v11, v5
	global_store_dwordx2 v[8:9], v[4:5], off offset:-3072
	v_lshl_add_u64 v[10:11], v[36:37], 0, v[34:35]
	v_mov_b32_e32 v10, v0
	v_mov_b32_e32 v11, v2
	v_pk_mul_f32 v[10:11], v[10:11], v[12:13] op_sel_hi:[1,0]
	v_mov_b32_e32 v2, v1
	v_pk_mul_f32 v[0:1], v[2:3], v[12:13] op_sel_hi:[1,0]
	s_waitcnt vmcnt(17)
	v_mov_b32_e32 v4, v164
	v_mov_b32_e32 v5, v165
	v_mov_b32_e32 v6, v166
	v_mov_b32_e32 v7, v167
	v_mov_b32_e32 v14, v4
	v_mov_b32_e32 v15, v6
	v_pk_mul_f32 v[10:11], v[10:11], v[14:15]
	s_waitcnt vmcnt(16)
	v_mov_b32_e32 v36, v168
	v_mov_b32_e32 v37, v169
	v_mov_b32_e32 v38, v170
	v_mov_b32_e32 v39, v171
	v_mov_b32_e32 v15, v38
	v_mov_b32_e32 v6, v5
	v_mov_b32_e32 v38, v37
	v_mov_b32_e32 v14, v36
	s_waitcnt vmcnt(15)
	v_mov_b32_e32 v48, v172
	v_mov_b32_e32 v49, v173
	v_mov_b32_e32 v50, v174
	v_mov_b32_e32 v51, v175
	v_mov_b32_e32 v53, v50
	v_pk_mul_f32 v[0:1], v[0:1], v[6:7]
	v_pk_add_f32 v[2:3], v[38:39], 1.0 op_sel_hi:[1,0]
	v_mov_b32_e32 v50, v49
	v_pk_add_f32 v[14:15], v[14:15], 1.0 op_sel_hi:[1,0]
	v_mov_b32_e32 v52, v48
	v_pk_fma_f32 v[0:1], v[0:1], v[2:3], v[50:51]
	v_pk_fma_f32 v[10:11], v[10:11], v[14:15], v[52:53]
	v_cvt_pk_bf16_f32 v1, v11, v1
	v_cvt_pk_bf16_f32 v0, v10, v0
	global_store_dwordx2 v[8:9], v[0:1], off offset:-2560
	s_andn2_b64 exec, exec, s[2:3]
	s_cbranch_execnz .LBB0_34
